# v62 + barrier 3 replaced by arrival counter + chunk-state scan moved to the 120 non-GEMM workgroups (+16 blocks on WGs 0..15) so it overlaps the glu GEMM
# speedup vs baseline: 1.0010x; 1.0002x over previous
; #define LAS __attribute__((address_space(3)))
; __device__ __forceinline__ void hg_scan(Frame& F, bf16* DSO, int sb, int nsb) {
;     ...
;     for (int T0 = sb * 512; T0 < 32 * 4096; T0 += nsb * 512) {
;         const int T = T0 + F.tid, bh = T0 >> 12, e = T & 4095, v = e >> 5, k4 = (e & 31) * 4;
;         v2u x[32];
; #pragma unroll
;         for (int c = 0; c < 32; ++c) x[c] = *(const v2u*)(DSC + ((size_t)(bh * 32 + c) * HD + v) * HD + k4);
; #pragma unroll
;         for (int i = 0; i < 2; ++i) { const int p = F.tid + 512 * i; *(LAS f32x4*)(DL + p * 4) = *(const f32x4*)(DEC + (size_t)bh * 32 * HD + p * 4); }
.LBB0_607:
	v_readlane_b32 s0, v238, 0
	v_readlane_b32 s1, v238, 1
	s_cmp_lt_i32 s0, 4
	s_cselect_b64 s[0:1], -1, 0
	s_and_b64 s[0:1], s[0:1], s[4:5]
	s_andn2_b64 vcc, exec, s[0:1]
	s_cbranch_vccnz .LBB0_611
	s_cmpk_gt_i32 s2, 0xff
	s_cbranch_scc1 .LBB0_611
	s_cmpk_lt_i32 s2, 16
	s_cbranch_scc1 my_scan_go
	s_cmpk_lt_i32 s2, 0x88
	s_cbranch_scc1 .LBB0_611
my_scan_go:
	v_lshlrev_b32_e32 v2, 2, v0
	v_and_b32_e32 v6, 0x7c, v2
	v_lshlrev_b32_e32 v2, 1, v6
	v_mov_b32_e32 v3, 0
	v_lshl_add_u64 v[4:5], s[46:47], 0, v[2:3]
	v_lshlrev_b32_e32 v2, 9, v6
	v_lshlrev_b32_e32 v8, 4, v0
	v_lshl_add_u32 v71, v6, 2, 0
	v_lshl_add_u64 v[6:7], s[48:49], 0, v[2:3]
	s_mov_b64 s[4:5], 0x4420000
	v_mov_b32_e32 v9, v3
	v_add_u32_e32 v70, 0, v8
	v_lshl_add_u64 v[6:7], v[6:7], 0, s[4:5]
	v_lshl_add_u64 v[8:9], s[50:51], 0, v[8:9]
	s_mov_b64 s[4:5], 0x100000
	s_sub_i32 s3, s2, 0x88
	s_add_i32 s12, s2, 0xf0
	s_cmpk_lt_i32 s2, 16
	s_cselect_b32 s3, s12, s3
	s_mov_b32 s12, 0x1e000
	s_cselect_b32 s12, 0x20000, s12
	s_lshl_b32 s3, s3, 9
	s_mov_b32 s8, 0xf000
	v_lshl_add_u64 v[8:9], v[8:9], 0, s[4:5]
	s_movk_i32 s9, 0x2000
	v_mov_b32_e32 v72, v3
	v_mov_b32_e32 v73, v3
.LBB0_610:
	v_add_u32_e32 v2, s3, v0
	s_ashr_i32 s4, s3, 12
	v_bfe_u32 v148, v2, 5, 7
	s_lshl_b32 s6, s4, 5
	v_lshlrev_b32_e32 v2, 8, v148
	s_ashr_i32 s7, s6, 31
	v_lshl_add_u64 v[10:11], v[4:5], 0, v[2:3]
	s_lshl_b64 s[10:11], s[6:7], 15
	v_lshl_add_u64 v[78:79], v[10:11], 0, s[10:11]
	s_or_b32 s10, s6, 1
	s_ashr_i32 s11, s10, 31
	s_lshl_b64 s[10:11], s[10:11], 15
	v_lshl_add_u64 v[82:83], v[10:11], 0, s[10:11]
	s_or_b32 s10, s6, 2
	s_ashr_i32 s11, s10, 31
	s_lshl_b64 s[10:11], s[10:11], 15
	v_lshl_add_u64 v[86:87], v[10:11], 0, s[10:11]
	s_or_b32 s10, s6, 3
	s_ashr_i32 s11, s10, 31
	s_lshl_b64 s[10:11], s[10:11], 15
	v_lshl_add_u64 v[90:91], v[10:11], 0, s[10:11]
	s_or_b32 s10, s6, 4
	s_ashr_i32 s11, s10, 31
	s_lshl_b64 s[10:11], s[10:11], 15
	v_lshl_add_u64 v[94:95], v[10:11], 0, s[10:11]
	s_or_b32 s10, s6, 5
	s_ashr_i32 s11, s10, 31
	s_lshl_b64 s[10:11], s[10:11], 15
	v_lshl_add_u64 v[98:99], v[10:11], 0, s[10:11]
	s_or_b32 s10, s6, 6
	s_ashr_i32 s11, s10, 31
	s_lshl_b64 s[10:11], s[10:11], 15
	v_lshl_add_u64 v[102:103], v[10:11], 0, s[10:11]
	s_or_b32 s10, s6, 7
	s_ashr_i32 s11, s10, 31
	s_lshl_b64 s[10:11], s[10:11], 15
	v_lshl_add_u64 v[106:107], v[10:11], 0, s[10:11]
	s_or_b32 s10, s6, 8
	s_ashr_i32 s11, s10, 31
	s_lshl_b64 s[10:11], s[10:11], 15
	v_lshl_add_u64 v[110:111], v[10:11], 0, s[10:11]
	s_or_b32 s10, s6, 9
	s_ashr_i32 s11, s10, 31
	s_lshl_b64 s[10:11], s[10:11], 15
	v_lshl_add_u64 v[114:115], v[10:11], 0, s[10:11]
	s_or_b32 s10, s6, 10
	s_ashr_i32 s11, s10, 31
	s_lshl_b64 s[10:11], s[10:11], 15
	v_lshl_add_u64 v[118:119], v[10:11], 0, s[10:11]
	s_or_b32 s10, s6, 11
	s_ashr_i32 s11, s10, 31
	s_lshl_b64 s[10:11], s[10:11], 15
	v_lshl_add_u64 v[122:123], v[10:11], 0, s[10:11]
	s_or_b32 s10, s6, 12
	s_ashr_i32 s11, s10, 31
	s_lshl_b64 s[10:11], s[10:11], 15
	v_lshl_add_u64 v[126:127], v[10:11], 0, s[10:11]
	s_or_b32 s10, s6, 13
	s_ashr_i32 s11, s10, 31
	s_lshl_b64 s[10:11], s[10:11], 15
	v_lshl_add_u64 v[130:131], v[10:11], 0, s[10:11]
	s_or_b32 s10, s6, 14
	s_ashr_i32 s11, s10, 31
	s_lshl_b64 s[10:11], s[10:11], 15
	v_lshl_add_u64 v[134:135], v[10:11], 0, s[10:11]
	s_or_b32 s10, s6, 15
	s_ashr_i32 s11, s10, 31
	s_lshl_b64 s[10:11], s[10:11], 15
	v_lshl_add_u64 v[138:139], v[10:11], 0, s[10:11]
	s_or_b32 s10, s6, 16
	s_ashr_i32 s11, s10, 31
	s_lshl_b64 s[10:11], s[10:11], 15
	v_lshl_add_u64 v[142:143], v[10:11], 0, s[10:11]
	s_or_b32 s10, s6, 17
	s_ashr_i32 s11, s10, 31
	s_lshl_b64 s[10:11], s[10:11], 15
	v_lshl_add_u64 v[68:69], v[10:11], 0, s[10:11]
	s_or_b32 s10, s6, 18
	s_ashr_i32 s11, s10, 31
	s_lshl_b64 s[10:11], s[10:11], 15
	v_lshl_add_u64 v[64:65], v[10:11], 0, s[10:11]
	s_or_b32 s10, s6, 19
	s_ashr_i32 s11, s10, 31
	s_lshl_b64 s[10:11], s[10:11], 15
	v_lshl_add_u64 v[60:61], v[10:11], 0, s[10:11]
	s_or_b32 s10, s6, 20
	s_ashr_i32 s11, s10, 31
	s_lshl_b64 s[10:11], s[10:11], 15
	v_lshl_add_u64 v[56:57], v[10:11], 0, s[10:11]
	s_or_b32 s10, s6, 21
	s_ashr_i32 s11, s10, 31
	s_lshl_b64 s[10:11], s[10:11], 15
	v_lshl_add_u64 v[52:53], v[10:11], 0, s[10:11]
	s_or_b32 s10, s6, 22
	s_ashr_i32 s11, s10, 31
	s_lshl_b64 s[10:11], s[10:11], 15
	v_lshl_add_u64 v[48:49], v[10:11], 0, s[10:11]
	s_or_b32 s10, s6, 23
	s_ashr_i32 s11, s10, 31
	s_lshl_b64 s[10:11], s[10:11], 15
	v_lshl_add_u64 v[44:45], v[10:11], 0, s[10:11]
	s_or_b32 s10, s6, 24
	s_ashr_i32 s11, s10, 31
	s_lshl_b64 s[10:11], s[10:11], 15
	v_lshl_add_u64 v[40:41], v[10:11], 0, s[10:11]
	s_or_b32 s10, s6, 25
	s_ashr_i32 s11, s10, 31
	s_lshl_b64 s[10:11], s[10:11], 15
	v_lshl_add_u64 v[36:37], v[10:11], 0, s[10:11]
	s_or_b32 s10, s6, 26
	s_ashr_i32 s11, s10, 31
	s_lshl_b64 s[10:11], s[10:11], 15
	v_lshl_add_u64 v[32:33], v[10:11], 0, s[10:11]
	s_or_b32 s10, s6, 27
	s_ashr_i32 s11, s10, 31
	s_lshl_b64 s[10:11], s[10:11], 15
	v_lshl_add_u64 v[28:29], v[10:11], 0, s[10:11]
	s_or_b32 s10, s6, 28
	s_ashr_i32 s11, s10, 31
	s_lshl_b64 s[10:11], s[10:11], 15
	s_waitcnt vmcnt(0)
; #define LAS __attribute__((address_space(3)))
; __device__ __forceinline__ unsigned pk2(float lo, float hi) { f32x2_t v = {lo, hi}; bf16x2_t h = __builtin_convertvector(v, bf16x2_t); return __builtin_bit_cast(unsigned, h); }
; __device__ __forceinline__ void hg_scan(Frame& F, bf16* DSO, int sb, int nsb) {
;     ...
;         const int T = T0 + F.tid, bh = T0 >> 12, e = T & 4095, v = e >> 5, k4 = (e & 31) * 4;
;         v2u x[32];
; #pragma unroll
;         for (int c = 0; c < 32; ++c) x[c] = *(const v2u*)(DSC + ((size_t)(bh * 32 + c) * HD + v) * HD + k4);
; #pragma unroll
;         for (int i = 0; i < 2; ++i) { const int p = F.tid + 512 * i; *(LAS f32x4*)(DL + p * 4) = *(const f32x4*)(DEC + (size_t)bh * 32 * HD + p * 4); }
;         __syncthreads();
;         f32x4 S = {0.f, 0.f, 0.f, 0.f};
; #pragma unroll
;         for (int c = 0; c < 32; ++c) { const f32x4 d = *(const LAS f32x4*)(DL + c * HD + k4);
;             v2u o; o.x = pk2(S.x, S.y); o.y = pk2(S.z, S.w); *(v2u*)(DSO + ((size_t)(bh * 32 + c) * HD + v) * HD + k4) = o;
;             S.x = d.x * S.x + bflo(x[c].x); S.y = d.y * S.y + bfhi(x[c].x); S.z = d.z * S.z + bflo(x[c].y); S.w = d.w * S.w + bfhi(x[c].y); }
	v_lshl_add_u64 v[24:25], v[10:11], 0, s[10:11]
	s_or_b32 s10, s6, 29
	s_ashr_i32 s11, s10, 31
	s_lshl_b64 s[10:11], s[10:11], 15
	v_lshl_add_u64 v[20:21], v[10:11], 0, s[10:11]
	s_or_b32 s10, s6, 30
	s_or_b32 s6, s6, 31
	s_ashr_i32 s7, s6, 31
	s_lshl_b64 s[6:7], s[6:7], 15
	s_ashr_i32 s5, s4, 31
	v_lshl_add_u64 v[12:13], v[10:11], 0, s[6:7]
	s_lshl_b64 s[6:7], s[4:5], 14
	v_lshl_add_u64 v[146:147], v[8:9], 0, s[6:7]
	global_load_dwordx4 v[74:77], v[146:147], off
	global_load_dwordx2 v[80:81], v[78:79], off
	global_load_dwordx2 v[84:85], v[82:83], off
	global_load_dwordx2 v[88:89], v[86:87], off
	global_load_dwordx2 v[92:93], v[90:91], off
	global_load_dwordx2 v[96:97], v[94:95], off
	global_load_dwordx2 v[100:101], v[98:99], off
	global_load_dwordx2 v[104:105], v[102:103], off
	global_load_dwordx2 v[108:109], v[106:107], off
	global_load_dwordx2 v[112:113], v[110:111], off
	global_load_dwordx2 v[116:117], v[114:115], off
	global_load_dwordx2 v[120:121], v[118:119], off
	global_load_dwordx2 v[124:125], v[122:123], off
	global_load_dwordx2 v[128:129], v[126:127], off
	s_ashr_i32 s11, s10, 31
	s_lshl_b64 s[10:11], s[10:11], 15
	v_lshl_add_u64 v[16:17], v[10:11], 0, s[10:11]
	global_load_dwordx2 v[132:133], v[130:131], off
	global_load_dwordx2 v[136:137], v[134:135], off
	global_load_dwordx2 v[140:141], v[138:139], off
	global_load_dwordx2 v[144:145], v[142:143], off
	global_load_dwordx2 v[66:67], v[68:69], off
	global_load_dwordx2 v[62:63], v[64:65], off
	global_load_dwordx2 v[58:59], v[60:61], off
	global_load_dwordx2 v[54:55], v[56:57], off
	global_load_dwordx2 v[50:51], v[52:53], off
	global_load_dwordx2 v[46:47], v[48:49], off
	global_load_dwordx2 v[42:43], v[44:45], off
	global_load_dwordx2 v[38:39], v[40:41], off
	global_load_dwordx2 v[34:35], v[36:37], off
	global_load_dwordx2 v[30:31], v[32:33], off
	global_load_dwordx2 v[26:27], v[28:29], off
	global_load_dwordx2 v[22:23], v[24:25], off
	global_load_dwordx2 v[18:19], v[20:21], off
	global_load_dwordx2 v[14:15], v[16:17], off
	global_load_dwordx2 v[10:11], v[12:13], off
	s_lshl_b64 s[4:5], s[4:5], 16
	v_lshlrev_b32_e32 v2, 2, v148
	s_add_i32 s3, s3, s8
	s_cmp_lt_i32 s3, s12
	s_waitcnt vmcnt(32)
	ds_write_b128 v70, v[74:77]
	v_add_co_u32_e32 v74, vcc, s9, v146
	s_nop 1
	v_addc_co_u32_e32 v75, vcc, 0, v147, vcc
	global_load_dwordx4 v[74:77], v[74:75], off
	s_waitcnt vmcnt(0)
	ds_write_b128 v70, v[74:77] offset:8192
	s_waitcnt lgkmcnt(0)
	s_barrier
	ds_read_b128 v[74:77], v71
	global_store_dwordx2 v[78:79], v[72:73], off sc1
	v_lshlrev_b32_e32 v78, 16, v80
	v_and_b32_e32 v79, 0xffff0000, v80
	s_waitcnt lgkmcnt(0)
	v_pk_fma_f32 v[78:79], v[74:75], 0, v[78:79] op_sel_hi:[1,0,1]
	v_lshlrev_b32_e32 v74, 16, v81
	v_and_b32_e32 v75, 0xffff0000, v81
	v_pk_fma_f32 v[80:81], v[76:77], 0, v[74:75] op_sel_hi:[1,0,1]
	ds_read_b128 v[74:77], v71 offset:512
	v_cvt_pk_bf16_f32 v146, v78, v79
	v_cvt_pk_bf16_f32 v147, v80, v81
	global_store_dwordx2 v[82:83], v[146:147], off sc1
	v_lshlrev_b32_e32 v82, 16, v84
	v_and_b32_e32 v83, 0xffff0000, v84
	s_waitcnt lgkmcnt(0)
	v_pk_fma_f32 v[78:79], v[78:79], v[74:75], v[82:83]
	v_lshlrev_b32_e32 v74, 16, v85
	v_and_b32_e32 v75, 0xffff0000, v85
	v_pk_fma_f32 v[80:81], v[80:81], v[76:77], v[74:75]
	ds_read_b128 v[74:77], v71 offset:1024
	v_cvt_pk_bf16_f32 v82, v78, v79
	v_cvt_pk_bf16_f32 v83, v80, v81
	global_store_dwordx2 v[86:87], v[82:83], off sc1
	v_lshlrev_b32_e32 v82, 16, v88
	v_and_b32_e32 v83, 0xffff0000, v88
	s_waitcnt lgkmcnt(0)
	v_pk_fma_f32 v[78:79], v[78:79], v[74:75], v[82:83]
	v_lshlrev_b32_e32 v74, 16, v89
	v_and_b32_e32 v75, 0xffff0000, v89
	v_pk_fma_f32 v[80:81], v[80:81], v[76:77], v[74:75]
	ds_read_b128 v[74:77], v71 offset:1536
	v_cvt_pk_bf16_f32 v82, v78, v79
	v_cvt_pk_bf16_f32 v83, v80, v81
	global_store_dwordx2 v[90:91], v[82:83], off sc1
	v_lshlrev_b32_e32 v82, 16, v92
	v_and_b32_e32 v83, 0xffff0000, v92
	s_waitcnt lgkmcnt(0)
	v_pk_fma_f32 v[78:79], v[78:79], v[74:75], v[82:83]
	v_lshlrev_b32_e32 v74, 16, v93
	v_and_b32_e32 v75, 0xffff0000, v93
	v_pk_fma_f32 v[80:81], v[80:81], v[76:77], v[74:75]
	ds_read_b128 v[74:77], v71 offset:2048
	v_cvt_pk_bf16_f32 v82, v78, v79
	v_cvt_pk_bf16_f32 v83, v80, v81
	global_store_dwordx2 v[94:95], v[82:83], off sc1
	v_lshlrev_b32_e32 v82, 16, v96
	v_and_b32_e32 v83, 0xffff0000, v96
	s_waitcnt lgkmcnt(0)
	v_pk_fma_f32 v[78:79], v[78:79], v[74:75], v[82:83]
	v_lshlrev_b32_e32 v74, 16, v97
	v_and_b32_e32 v75, 0xffff0000, v97
	v_pk_fma_f32 v[80:81], v[80:81], v[76:77], v[74:75]
	ds_read_b128 v[74:77], v71 offset:2560
	v_cvt_pk_bf16_f32 v82, v78, v79
	v_cvt_pk_bf16_f32 v83, v80, v81
	global_store_dwordx2 v[98:99], v[82:83], off sc1
	v_lshlrev_b32_e32 v82, 16, v100
	v_and_b32_e32 v83, 0xffff0000, v100
	s_waitcnt lgkmcnt(0)
	v_pk_fma_f32 v[78:79], v[78:79], v[74:75], v[82:83]
	v_lshlrev_b32_e32 v74, 16, v101
	v_and_b32_e32 v75, 0xffff0000, v101
	v_pk_fma_f32 v[80:81], v[80:81], v[76:77], v[74:75]
	ds_read_b128 v[74:77], v71 offset:3072
	v_cvt_pk_bf16_f32 v82, v78, v79
	v_cvt_pk_bf16_f32 v83, v80, v81
	global_store_dwordx2 v[102:103], v[82:83], off sc1
	v_lshlrev_b32_e32 v82, 16, v104
	v_and_b32_e32 v83, 0xffff0000, v104
	s_waitcnt lgkmcnt(0)
	v_pk_fma_f32 v[78:79], v[78:79], v[74:75], v[82:83]
	v_lshlrev_b32_e32 v74, 16, v105
	v_and_b32_e32 v75, 0xffff0000, v105
	v_pk_fma_f32 v[80:81], v[80:81], v[76:77], v[74:75]
	ds_read_b128 v[74:77], v71 offset:3584
	v_cvt_pk_bf16_f32 v82, v78, v79
	v_cvt_pk_bf16_f32 v83, v80, v81
	global_store_dwordx2 v[106:107], v[82:83], off sc1
	v_lshlrev_b32_e32 v82, 16, v108
	v_and_b32_e32 v83, 0xffff0000, v108
	s_waitcnt lgkmcnt(0)
; #define LAS __attribute__((address_space(3)))
; __device__ __forceinline__ unsigned pk2(float lo, float hi) { f32x2_t v = {lo, hi}; bf16x2_t h = __builtin_convertvector(v, bf16x2_t); return __builtin_bit_cast(unsigned, h); }
; __device__ __forceinline__ void hg_scan(Frame& F, bf16* DSO, int sb, int nsb) {
;     ...
;         for (int c = 0; c < 32; ++c) { const f32x4 d = *(const LAS f32x4*)(DL + c * HD + k4);
;             v2u o; o.x = pk2(S.x, S.y); o.y = pk2(S.z, S.w); *(v2u*)(DSO + ((size_t)(bh * 32 + c) * HD + v) * HD + k4) = o;
;             S.x = d.x * S.x + bflo(x[c].x); S.y = d.y * S.y + bfhi(x[c].x); S.z = d.z * S.z + bflo(x[c].y); S.w = d.w * S.w + bfhi(x[c].y); }
	v_pk_fma_f32 v[78:79], v[78:79], v[74:75], v[82:83]
	v_lshlrev_b32_e32 v74, 16, v109
	v_and_b32_e32 v75, 0xffff0000, v109
	v_pk_fma_f32 v[80:81], v[80:81], v[76:77], v[74:75]
	ds_read_b128 v[74:77], v71 offset:4096
	v_cvt_pk_bf16_f32 v82, v78, v79
	v_cvt_pk_bf16_f32 v83, v80, v81
	global_store_dwordx2 v[110:111], v[82:83], off sc1
	v_lshlrev_b32_e32 v82, 16, v112
	v_and_b32_e32 v83, 0xffff0000, v112
	s_waitcnt lgkmcnt(0)
	v_pk_fma_f32 v[78:79], v[78:79], v[74:75], v[82:83]
	v_lshlrev_b32_e32 v74, 16, v113
	v_and_b32_e32 v75, 0xffff0000, v113
	v_pk_fma_f32 v[80:81], v[80:81], v[76:77], v[74:75]
	ds_read_b128 v[74:77], v71 offset:4608
	v_cvt_pk_bf16_f32 v82, v78, v79
	v_cvt_pk_bf16_f32 v83, v80, v81
	global_store_dwordx2 v[114:115], v[82:83], off sc1
	v_lshlrev_b32_e32 v82, 16, v116
	v_and_b32_e32 v83, 0xffff0000, v116
	s_waitcnt lgkmcnt(0)
	v_pk_fma_f32 v[78:79], v[78:79], v[74:75], v[82:83]
	v_lshlrev_b32_e32 v74, 16, v117
	v_and_b32_e32 v75, 0xffff0000, v117
	v_pk_fma_f32 v[80:81], v[80:81], v[76:77], v[74:75]
	ds_read_b128 v[74:77], v71 offset:5120
	v_cvt_pk_bf16_f32 v82, v78, v79
	v_cvt_pk_bf16_f32 v83, v80, v81
	global_store_dwordx2 v[118:119], v[82:83], off sc1
	v_lshlrev_b32_e32 v82, 16, v120
	v_and_b32_e32 v83, 0xffff0000, v120
	s_waitcnt lgkmcnt(0)
	v_pk_fma_f32 v[78:79], v[78:79], v[74:75], v[82:83]
	v_lshlrev_b32_e32 v74, 16, v121
	v_and_b32_e32 v75, 0xffff0000, v121
	v_pk_fma_f32 v[80:81], v[80:81], v[76:77], v[74:75]
	ds_read_b128 v[74:77], v71 offset:5632
	v_cvt_pk_bf16_f32 v82, v78, v79
	v_cvt_pk_bf16_f32 v83, v80, v81
	global_store_dwordx2 v[122:123], v[82:83], off sc1
	v_lshlrev_b32_e32 v82, 16, v124
	v_and_b32_e32 v83, 0xffff0000, v124
	s_waitcnt lgkmcnt(0)
	v_pk_fma_f32 v[78:79], v[78:79], v[74:75], v[82:83]
	v_lshlrev_b32_e32 v74, 16, v125
	v_and_b32_e32 v75, 0xffff0000, v125
	v_pk_fma_f32 v[80:81], v[80:81], v[76:77], v[74:75]
	ds_read_b128 v[74:77], v71 offset:6144
	v_cvt_pk_bf16_f32 v82, v78, v79
	v_cvt_pk_bf16_f32 v83, v80, v81
	global_store_dwordx2 v[126:127], v[82:83], off sc1
	v_lshlrev_b32_e32 v82, 16, v128
	v_and_b32_e32 v83, 0xffff0000, v128
	s_waitcnt lgkmcnt(0)
	v_pk_fma_f32 v[78:79], v[78:79], v[74:75], v[82:83]
	v_lshlrev_b32_e32 v74, 16, v129
	v_and_b32_e32 v75, 0xffff0000, v129
	v_pk_fma_f32 v[80:81], v[80:81], v[76:77], v[74:75]
	ds_read_b128 v[74:77], v71 offset:6656
	v_cvt_pk_bf16_f32 v82, v78, v79
	v_cvt_pk_bf16_f32 v83, v80, v81
	global_store_dwordx2 v[130:131], v[82:83], off sc1
	v_lshlrev_b32_e32 v82, 16, v132
	v_and_b32_e32 v83, 0xffff0000, v132
	s_waitcnt lgkmcnt(0)
	v_pk_fma_f32 v[78:79], v[78:79], v[74:75], v[82:83]
	v_lshlrev_b32_e32 v74, 16, v133
	v_and_b32_e32 v75, 0xffff0000, v133
	v_pk_fma_f32 v[80:81], v[80:81], v[76:77], v[74:75]
	ds_read_b128 v[74:77], v71 offset:7168
	v_cvt_pk_bf16_f32 v82, v78, v79
	v_cvt_pk_bf16_f32 v83, v80, v81
	global_store_dwordx2 v[134:135], v[82:83], off sc1
	v_lshlrev_b32_e32 v82, 16, v136
	v_and_b32_e32 v83, 0xffff0000, v136
	s_waitcnt lgkmcnt(0)
	v_pk_fma_f32 v[78:79], v[78:79], v[74:75], v[82:83]
	v_lshlrev_b32_e32 v74, 16, v137
	v_and_b32_e32 v75, 0xffff0000, v137
	v_pk_fma_f32 v[80:81], v[80:81], v[76:77], v[74:75]
	ds_read_b128 v[74:77], v71 offset:7680
	v_cvt_pk_bf16_f32 v82, v78, v79
	v_cvt_pk_bf16_f32 v83, v80, v81
	global_store_dwordx2 v[138:139], v[82:83], off sc1
	v_lshlrev_b32_e32 v82, 16, v140
	v_and_b32_e32 v83, 0xffff0000, v140
	s_waitcnt lgkmcnt(0)
	v_pk_fma_f32 v[78:79], v[78:79], v[74:75], v[82:83]
	v_lshlrev_b32_e32 v74, 16, v141
	v_and_b32_e32 v75, 0xffff0000, v141
	v_pk_fma_f32 v[80:81], v[80:81], v[76:77], v[74:75]
	ds_read_b128 v[74:77], v71 offset:8192
	v_cvt_pk_bf16_f32 v82, v78, v79
	v_cvt_pk_bf16_f32 v83, v80, v81
	global_store_dwordx2 v[142:143], v[82:83], off sc1
	v_lshlrev_b32_e32 v82, 16, v144
	v_and_b32_e32 v83, 0xffff0000, v144
	s_waitcnt lgkmcnt(0)
	v_pk_fma_f32 v[78:79], v[78:79], v[74:75], v[82:83]
	v_lshlrev_b32_e32 v74, 16, v145
	v_and_b32_e32 v75, 0xffff0000, v145
	v_pk_fma_f32 v[80:81], v[80:81], v[76:77], v[74:75]
	ds_read_b128 v[74:77], v71 offset:8704
	v_cvt_pk_bf16_f32 v82, v78, v79
	v_cvt_pk_bf16_f32 v83, v80, v81
	global_store_dwordx2 v[68:69], v[82:83], off sc1
	v_lshlrev_b32_e32 v68, 16, v66
	v_and_b32_e32 v69, 0xffff0000, v66
	v_lshlrev_b32_e32 v66, 16, v67
	v_and_b32_e32 v67, 0xffff0000, v67
	s_waitcnt lgkmcnt(0)
	v_pk_fma_f32 v[74:75], v[78:79], v[74:75], v[68:69]
	v_pk_fma_f32 v[76:77], v[80:81], v[76:77], v[66:67]
	ds_read_b128 v[66:69], v71 offset:9216
	v_cvt_pk_bf16_f32 v78, v74, v75
	v_cvt_pk_bf16_f32 v79, v76, v77
	global_store_dwordx2 v[64:65], v[78:79], off sc1
	v_lshlrev_b32_e32 v64, 16, v62
	v_and_b32_e32 v65, 0xffff0000, v62
	v_lshlrev_b32_e32 v62, 16, v63
	v_and_b32_e32 v63, 0xffff0000, v63
	s_waitcnt lgkmcnt(0)
	v_pk_fma_f32 v[66:67], v[74:75], v[66:67], v[64:65]
	v_pk_fma_f32 v[68:69], v[76:77], v[68:69], v[62:63]
	ds_read_b128 v[62:65], v71 offset:9728
	v_cvt_pk_bf16_f32 v74, v66, v67
	v_cvt_pk_bf16_f32 v75, v68, v69
	global_store_dwordx2 v[60:61], v[74:75], off sc1
	v_lshlrev_b32_e32 v60, 16, v58
	v_and_b32_e32 v61, 0xffff0000, v58
	v_lshlrev_b32_e32 v58, 16, v59
	v_and_b32_e32 v59, 0xffff0000, v59
	s_waitcnt lgkmcnt(0)
; #define LAS __attribute__((address_space(3)))
; __device__ __forceinline__ unsigned pk2(float lo, float hi) { f32x2_t v = {lo, hi}; bf16x2_t h = __builtin_convertvector(v, bf16x2_t); return __builtin_bit_cast(unsigned, h); }
; __device__ __forceinline__ void hg_scan(Frame& F, bf16* DSO, int sb, int nsb) {
;     ...
;         for (int c = 0; c < 32; ++c) { const f32x4 d = *(const LAS f32x4*)(DL + c * HD + k4);
;             v2u o; o.x = pk2(S.x, S.y); o.y = pk2(S.z, S.w); *(v2u*)(DSO + ((size_t)(bh * 32 + c) * HD + v) * HD + k4) = o;
;             S.x = d.x * S.x + bflo(x[c].x); S.y = d.y * S.y + bfhi(x[c].x); S.z = d.z * S.z + bflo(x[c].y); S.w = d.w * S.w + bfhi(x[c].y); }
;         float* o = F.out + O_PHG + (size_t)bh * HD * HD + (size_t)k4 * HD + v;
;         o[0] = S.x; o[HD] = S.y; o[2 * HD] = S.z; o[3 * HD] = S.w;
	v_pk_fma_f32 v[62:63], v[66:67], v[62:63], v[60:61]
	v_pk_fma_f32 v[64:65], v[68:69], v[64:65], v[58:59]
	ds_read_b128 v[58:61], v71 offset:10240
	v_cvt_pk_bf16_f32 v66, v62, v63
	v_cvt_pk_bf16_f32 v67, v64, v65
	global_store_dwordx2 v[56:57], v[66:67], off sc1
	v_lshlrev_b32_e32 v56, 16, v54
	v_and_b32_e32 v57, 0xffff0000, v54
	v_lshlrev_b32_e32 v54, 16, v55
	v_and_b32_e32 v55, 0xffff0000, v55
	s_waitcnt lgkmcnt(0)
	v_pk_fma_f32 v[58:59], v[62:63], v[58:59], v[56:57]
	v_pk_fma_f32 v[60:61], v[64:65], v[60:61], v[54:55]
	ds_read_b128 v[54:57], v71 offset:10752
	v_cvt_pk_bf16_f32 v62, v58, v59
	v_cvt_pk_bf16_f32 v63, v60, v61
	global_store_dwordx2 v[52:53], v[62:63], off sc1
	v_lshlrev_b32_e32 v52, 16, v50
	v_and_b32_e32 v53, 0xffff0000, v50
	v_lshlrev_b32_e32 v50, 16, v51
	v_and_b32_e32 v51, 0xffff0000, v51
	s_waitcnt lgkmcnt(0)
	v_pk_fma_f32 v[54:55], v[58:59], v[54:55], v[52:53]
	v_pk_fma_f32 v[56:57], v[60:61], v[56:57], v[50:51]
	ds_read_b128 v[50:53], v71 offset:11264
	v_cvt_pk_bf16_f32 v58, v54, v55
	v_cvt_pk_bf16_f32 v59, v56, v57
	global_store_dwordx2 v[48:49], v[58:59], off sc1
	v_lshlrev_b32_e32 v48, 16, v46
	v_and_b32_e32 v49, 0xffff0000, v46
	v_lshlrev_b32_e32 v46, 16, v47
	v_and_b32_e32 v47, 0xffff0000, v47
	s_waitcnt lgkmcnt(0)
	v_pk_fma_f32 v[50:51], v[54:55], v[50:51], v[48:49]
	v_pk_fma_f32 v[52:53], v[56:57], v[52:53], v[46:47]
	ds_read_b128 v[46:49], v71 offset:11776
	v_cvt_pk_bf16_f32 v54, v50, v51
	v_cvt_pk_bf16_f32 v55, v52, v53
	global_store_dwordx2 v[44:45], v[54:55], off sc1
	v_lshlrev_b32_e32 v44, 16, v42
	v_and_b32_e32 v45, 0xffff0000, v42
	v_lshlrev_b32_e32 v42, 16, v43
	v_and_b32_e32 v43, 0xffff0000, v43
	s_waitcnt lgkmcnt(0)
	v_pk_fma_f32 v[46:47], v[50:51], v[46:47], v[44:45]
	v_pk_fma_f32 v[48:49], v[52:53], v[48:49], v[42:43]
	ds_read_b128 v[42:45], v71 offset:12288
	v_cvt_pk_bf16_f32 v50, v46, v47
	v_cvt_pk_bf16_f32 v51, v48, v49
	global_store_dwordx2 v[40:41], v[50:51], off sc1
	v_lshlrev_b32_e32 v40, 16, v38
	v_and_b32_e32 v41, 0xffff0000, v38
	v_lshlrev_b32_e32 v38, 16, v39
	v_and_b32_e32 v39, 0xffff0000, v39
	s_waitcnt lgkmcnt(0)
	v_pk_fma_f32 v[42:43], v[46:47], v[42:43], v[40:41]
	v_pk_fma_f32 v[44:45], v[48:49], v[44:45], v[38:39]
	ds_read_b128 v[38:41], v71 offset:12800
	v_cvt_pk_bf16_f32 v46, v42, v43
	v_cvt_pk_bf16_f32 v47, v44, v45
	global_store_dwordx2 v[36:37], v[46:47], off sc1
	v_lshlrev_b32_e32 v36, 16, v34
	v_and_b32_e32 v37, 0xffff0000, v34
	v_lshlrev_b32_e32 v34, 16, v35
	v_and_b32_e32 v35, 0xffff0000, v35
	s_waitcnt lgkmcnt(0)
	v_pk_fma_f32 v[38:39], v[42:43], v[38:39], v[36:37]
	v_pk_fma_f32 v[40:41], v[44:45], v[40:41], v[34:35]
	ds_read_b128 v[34:37], v71 offset:13312
	v_cvt_pk_bf16_f32 v42, v38, v39
	v_cvt_pk_bf16_f32 v43, v40, v41
	global_store_dwordx2 v[32:33], v[42:43], off sc1
	v_lshlrev_b32_e32 v32, 16, v30
	v_and_b32_e32 v33, 0xffff0000, v30
	v_lshlrev_b32_e32 v30, 16, v31
	v_and_b32_e32 v31, 0xffff0000, v31
	s_waitcnt lgkmcnt(0)
	v_pk_fma_f32 v[34:35], v[38:39], v[34:35], v[32:33]
	v_pk_fma_f32 v[36:37], v[40:41], v[36:37], v[30:31]
	ds_read_b128 v[30:33], v71 offset:13824
	v_cvt_pk_bf16_f32 v38, v34, v35
	v_cvt_pk_bf16_f32 v39, v36, v37
	global_store_dwordx2 v[28:29], v[38:39], off sc1
	v_lshlrev_b32_e32 v28, 16, v26
	v_and_b32_e32 v29, 0xffff0000, v26
	v_lshlrev_b32_e32 v26, 16, v27
	v_and_b32_e32 v27, 0xffff0000, v27
	s_waitcnt lgkmcnt(0)
	v_pk_fma_f32 v[30:31], v[34:35], v[30:31], v[28:29]
	v_pk_fma_f32 v[32:33], v[36:37], v[32:33], v[26:27]
	ds_read_b128 v[26:29], v71 offset:14336
	v_cvt_pk_bf16_f32 v34, v30, v31
	v_cvt_pk_bf16_f32 v35, v32, v33
	global_store_dwordx2 v[24:25], v[34:35], off sc1
	v_lshlrev_b32_e32 v24, 16, v22
	v_and_b32_e32 v25, 0xffff0000, v22
	v_lshlrev_b32_e32 v22, 16, v23
	v_and_b32_e32 v23, 0xffff0000, v23
	s_waitcnt lgkmcnt(0)
	v_pk_fma_f32 v[26:27], v[30:31], v[26:27], v[24:25]
	v_pk_fma_f32 v[28:29], v[32:33], v[28:29], v[22:23]
	ds_read_b128 v[22:25], v71 offset:14848
	v_cvt_pk_bf16_f32 v30, v26, v27
	v_cvt_pk_bf16_f32 v31, v28, v29
	global_store_dwordx2 v[20:21], v[30:31], off sc1
	v_lshlrev_b32_e32 v20, 16, v18
	v_and_b32_e32 v21, 0xffff0000, v18
	v_lshlrev_b32_e32 v18, 16, v19
	v_and_b32_e32 v19, 0xffff0000, v19
	s_waitcnt lgkmcnt(0)
	v_pk_fma_f32 v[22:23], v[26:27], v[22:23], v[20:21]
	v_pk_fma_f32 v[24:25], v[28:29], v[24:25], v[18:19]
	ds_read_b128 v[18:21], v71 offset:15360
	v_cvt_pk_bf16_f32 v26, v22, v23
	v_cvt_pk_bf16_f32 v27, v24, v25
	global_store_dwordx2 v[16:17], v[26:27], off sc1
	v_lshlrev_b32_e32 v16, 16, v14
	v_and_b32_e32 v17, 0xffff0000, v14
	v_lshlrev_b32_e32 v14, 16, v15
	v_and_b32_e32 v15, 0xffff0000, v15
	s_waitcnt lgkmcnt(0)
	v_pk_fma_f32 v[18:19], v[22:23], v[18:19], v[16:17]
	v_pk_fma_f32 v[20:21], v[24:25], v[20:21], v[14:15]
	ds_read_b128 v[14:17], v71 offset:15872
	v_cvt_pk_bf16_f32 v22, v18, v19
	v_cvt_pk_bf16_f32 v23, v20, v21
	global_store_dwordx2 v[12:13], v[22:23], off sc1
	v_lshlrev_b32_e32 v12, 16, v10
	v_and_b32_e32 v13, 0xffff0000, v10
	s_waitcnt lgkmcnt(0)
	v_fmac_f32_e32 v12, v18, v14
	v_fmac_f32_e32 v13, v19, v15
	v_lshlrev_b32_e32 v14, 16, v11
	v_and_b32_e32 v15, 0xffff0000, v11
	v_lshl_add_u64 v[10:11], v[6:7], 0, s[4:5]
	v_lshl_add_u64 v[10:11], v[10:11], 0, v[2:3]
	v_fmac_f32_e32 v14, v20, v16
	v_fmac_f32_e32 v15, v21, v17
	global_store_dword v[10:11], v12, off
	global_store_dword v[10:11], v13, off offset:512
	global_store_dword v[10:11], v14, off offset:1024
	global_store_dword v[10:11], v15, off offset:1536
	s_barrier
	s_cbranch_scc1 .LBB0_610
